# attention: per-lane local max + ballot in common path; cross-lane max only in rare rescale path; drop canonicalizing max
# baseline (speedup 1.0000x reference)
; template <int MODE  , int QLO, int QHI> ...
;     ...
;         float tmax[4];
; #pragma unroll
;         for (int qt = QLO; qt < QHI; ++qt) {
;             const float a = fmaxf(fmaxf(fmaxf(sA[qt][0], sA[qt][1]), fmaxf(sA[qt][2], sA[qt][3])), fmaxf(fmaxf(sB[qt][0], sB[qt][1]), fmaxf(sB[qt][2], sB[qt][3])));
;             tmax[qt] = xmax16_32(a);
;         }
;         bool need = false;
; #pragma unroll
;         for (int qt = QLO; qt < QHI; ++qt) need = need || (tmax[qt] > mrun[qt] + 8.f);
;         if (__builtin_amdgcn_ballot_w64(need) != 0ull) {
; #pragma unroll
;             for (int qt = QLO; qt < QHI; ++qt) {
;                 const float mnew = fmaxf(mrun[qt], tmax[qt]); const float alpha = __builtin_amdgcn_exp2f(mrun[qt] - mnew);
;                 mrun[qt] = mnew; lrun[qt] *= alpha;
; #pragma unroll
;                 for (int dt = 0; dt < 4; ++dt) O[qt][dt] = O[qt][dt] * alpha;
;             }
;         }
.LBB0_587:
	v_max3_f32 v161, v156, v157, v158
	v_max3_f32 v195, v159, v152, v153
	v_max3_f32 v161, v161, v154, v155
	v_max_f32_e32 v197, v161, v195
	v_max3_f32 v161, v148, v149, v150
	v_max3_f32 v195, v151, v144, v145
	v_max3_f32 v161, v161, v146, v147
	v_max_f32_e32 v196, v161, v195
	v_max3_f32 v161, v140, v141, v142
	v_max3_f32 v195, v143, v136, v137
	v_max3_f32 v161, v161, v138, v139
	v_max_f32_e32 v195, v161, v195
	v_max3_f32 v161, v128, v129, v130
	v_max3_f32 v198, v131, v132, v133
	v_max3_f32 v161, v161, v134, v135
	v_max_f32_e32 v161, v161, v198
	v_add_f32_e32 v198, 0x41000000, v194
	v_cmp_gt_f32_e32 vcc, v197, v198
	v_add_f32_e32 v198, 0x41000000, v193
	v_cmp_gt_f32_e64 s[0:1], v196, v198
	v_add_f32_e32 v198, 0x41000000, v192
	s_or_b64 s[0:1], vcc, s[0:1]
	v_cmp_gt_f32_e32 vcc, v195, v198
	v_add_f32_e32 v198, 0x41000000, v167
	s_or_b64 s[0:1], s[0:1], vcc
	v_cmp_gt_f32_e32 vcc, v161, v198
	s_or_b64 vcc, s[0:1], vcc
	s_cbranch_vccz .LBB0_589
	v_mov_b32_e32 v198, v197
	s_nop 1
	v_permlane16_swap_b32_e32 v197, v198
	v_max_f32_e32 v197, v197, v198
	v_mov_b32_e32 v198, v197
	s_nop 1
	v_permlane32_swap_b32_e32 v197, v198
	v_max_f32_e32 v197, v197, v198
	v_mov_b32_e32 v198, v196
	s_nop 1
	v_permlane16_swap_b32_e32 v196, v198
	v_max_f32_e32 v196, v196, v198
	v_mov_b32_e32 v198, v196
	s_nop 1
	v_permlane32_swap_b32_e32 v196, v198
	v_max_f32_e32 v196, v196, v198
	v_mov_b32_e32 v198, v195
	s_nop 1
	v_permlane16_swap_b32_e32 v195, v198
	v_max_f32_e32 v195, v195, v198
	v_mov_b32_e32 v198, v195
	s_nop 1
	v_permlane32_swap_b32_e32 v195, v198
	v_max_f32_e32 v195, v195, v198
	v_mov_b32_e32 v198, v161
	s_nop 1
	v_permlane16_swap_b32_e32 v161, v198
	v_max_f32_e32 v161, v161, v198
	v_mov_b32_e32 v198, v161
	s_nop 1
	v_permlane32_swap_b32_e32 v161, v198
	v_max_f32_e32 v161, v161, v198
	v_max_f32_e32 v197, v197, v197
	v_max_f32_e32 v198, v194, v194
	v_max_f32_e32 v197, v198, v197
	v_sub_f32_e32 v194, v194, v197
	v_exp_f32_e32 v198, v194
	v_max_f32_e32 v194, v196, v196
	v_max_f32_e32 v196, v193, v193
	v_max_f32_e32 v196, v196, v194
	v_sub_f32_e32 v193, v193, v196
	v_pk_mul_f32 v[62:63], v[62:63], v[198:199] op_sel_hi:[1,0]
	v_pk_mul_f32 v[60:61], v[60:61], v[198:199] op_sel_hi:[1,0]
	v_pk_mul_f32 v[58:59], v[58:59], v[198:199] op_sel_hi:[1,0]
	v_pk_mul_f32 v[56:57], v[56:57], v[198:199] op_sel_hi:[1,0]
	v_pk_mul_f32 v[54:55], v[54:55], v[198:199] op_sel_hi:[1,0]
	v_pk_mul_f32 v[52:53], v[52:53], v[198:199] op_sel_hi:[1,0]
	v_pk_mul_f32 v[50:51], v[50:51], v[198:199] op_sel_hi:[1,0]
	v_pk_mul_f32 v[48:49], v[48:49], v[198:199] op_sel_hi:[1,0]
	v_exp_f32_e32 v199, v193
	v_max_f32_e32 v193, v195, v195
	v_max_f32_e32 v161, v161, v161
	v_mov_b32_e32 v194, v199
	v_pk_mul_f32 v[46:47], v[46:47], v[194:195] op_sel_hi:[1,0]
	v_pk_mul_f32 v[44:45], v[44:45], v[194:195] op_sel_hi:[1,0]
	v_max_f32_e32 v195, v192, v192
	v_max_f32_e32 v195, v195, v193
	v_sub_f32_e32 v192, v192, v195
	v_exp_f32_e32 v192, v192
	v_pk_mul_f32 v[178:179], v[178:179], v[198:199]
	v_pk_mul_f32 v[42:43], v[42:43], v[194:195] op_sel_hi:[1,0]
	v_pk_mul_f32 v[40:41], v[40:41], v[194:195] op_sel_hi:[1,0]
	v_pk_mul_f32 v[30:31], v[30:31], v[192:193] op_sel_hi:[1,0]
	v_pk_mul_f32 v[28:29], v[28:29], v[192:193] op_sel_hi:[1,0]
	v_pk_mul_f32 v[26:27], v[26:27], v[192:193] op_sel_hi:[1,0]
	v_pk_mul_f32 v[24:25], v[24:25], v[192:193] op_sel_hi:[1,0]
	v_pk_mul_f32 v[22:23], v[22:23], v[192:193] op_sel_hi:[1,0]
	v_pk_mul_f32 v[20:21], v[20:21], v[192:193] op_sel_hi:[1,0]
	v_pk_mul_f32 v[18:19], v[18:19], v[192:193] op_sel_hi:[1,0]
	v_pk_mul_f32 v[16:17], v[16:17], v[192:193] op_sel_hi:[1,0]
	v_max_f32_e32 v193, v167, v167
	v_max_f32_e32 v161, v193, v161
	v_sub_f32_e32 v167, v167, v161
	v_exp_f32_e32 v193, v167
	v_pk_mul_f32 v[38:39], v[38:39], v[194:195] op_sel_hi:[1,0]
	v_pk_mul_f32 v[36:37], v[36:37], v[194:195] op_sel_hi:[1,0]
	v_pk_mul_f32 v[34:35], v[34:35], v[194:195] op_sel_hi:[1,0]
	v_pk_mul_f32 v[170:171], v[170:171], v[192:193]
	v_mov_b32_e32 v192, v193
	v_pk_mul_f32 v[32:33], v[32:33], v[194:195] op_sel_hi:[1,0]
	v_pk_mul_f32 v[14:15], v[14:15], v[192:193] op_sel_hi:[1,0]
	v_pk_mul_f32 v[12:13], v[12:13], v[192:193] op_sel_hi:[1,0]
	v_pk_mul_f32 v[10:11], v[10:11], v[192:193] op_sel_hi:[1,0]
	v_pk_mul_f32 v[8:9], v[8:9], v[192:193] op_sel_hi:[1,0]
	v_pk_mul_f32 v[6:7], v[6:7], v[192:193] op_sel_hi:[1,0]
	v_pk_mul_f32 v[4:5], v[4:5], v[192:193] op_sel_hi:[1,0]
	v_pk_mul_f32 v[2:3], v[2:3], v[192:193] op_sel_hi:[1,0]
	v_pk_mul_f32 v[0:1], v[0:1], v[192:193] op_sel_hi:[1,0]
	v_mov_b32_e32 v167, v161
	v_mov_b32_e32 v192, v195
	v_mov_b32_e32 v193, v196
	v_mov_b32_e32 v194, v197

; template <int MODE  , int QLO, int QHI> ...
;     ...
;         for (int qt = QLO; qt < QHI; ++qt) {
;             const float a = fmaxf(fmaxf(fmaxf(sA[qt][0], sA[qt][1]), fmaxf(sA[qt][2], sA[qt][3])), fmaxf(fmaxf(sB[qt][0], sB[qt][1]), fmaxf(sB[qt][2], sB[qt][3])));
;             tmax[qt] = xmax16_32(a);
;         }
; template <int MODE, int DRY, int QLO, int QHI>
; __device__ __forceinline__ int attn_step(int o, int& par, const AttnCtx& C, const AttnLane& L, f32x4 (&O)[4][4], float (&mrun)[4], float (&lrun)[4], const bf16x8 (&Qf)[4][2], bf16x8 (&Kn)[4]) {
;     ...
;     int rk, jtA; bool same; pair_decode(pi, C.r4, C.j0, rk, jtA, same);
;     const int jtB = jtA + 16;
;     const bool vA = (jtA >= 0) && (jtA < 2048), vB = (jtB >= 0) && (jtB < 2048);
;     const int dr = rk - C.r4;
;     int on = o + 1; while (on < 27 && !pair_valid(order_pair(on), C.r4, C.j0)) ++on;
;     const int pn = order_pair(on < 27 ? on : 0);
;     asm volatile("s_waitcnt vmcnt(0)" ::: "memory");
;     bf16x8 Vf[4];
;     { LAS const unsigned char* vb = C.vl + par * 4096 + (4 * fq + (fr >> 2)) * 64 + (fr & 3) * 8;
; #pragma unroll
;       for (int dt = 0; dt < 4; ++dt) { const s16x4 lo = vtr(vb + (dt >> 1) * 1024 + (dt & 1) * 32), hi = vtr(vb + 2048 + (dt >> 1) * 1024 + (dt & 1) * 32);
;           Vf[dt] = (bf16x8){lo[0], lo[1], lo[2], lo[3], hi[0], hi[1], hi[2], hi[3]}; }
;       asm volatile("" ::: "memory"); }
;     if (DRY != 2) if (on < 27) attn_dma_v(pn, C.r4, C.j0, C.rowbase, C.h, C.vlo, C.Vr, C.vl + (par ^ 1) * 4096);
;     par ^= 1;
;     if (DRY == 1) {
;         asm volatile("" :: "v"(Kn[0]), "v"(Kn[1]), "v"(Kn[2]), "v"(Kn[3]), "v"(Vf[0]), "v"(Vf[1]), "v"(Vf[2]), "v"(Vf[3]));
;         if (on < 27) attn_load_k(pn, C.r4, C.j0, C.rowbase, C.h, C.klo, C.Kr, Kn);
;         return on;
;     }
;     f32x4 sA[4], sB[4];
; #pragma unroll
;     for (int qt = QLO; qt < QHI; ++qt) {
;         sA[qt] = __builtin_amdgcn_mfma_f32_16x16x32_bf16(Kn[0], Qf[qt][0], (f32x4){0.f, 0.f, 0.f, 0.f}, 0, 0, 0); sA[qt] = __builtin_amdgcn_mfma_f32_16x16x32_bf16(Kn[1], Qf[qt][1], sA[qt], 0, 0, 0);
;         sB[qt] = __builtin_amdgcn_mfma_f32_16x16x32_bf16(Kn[2], Qf[qt][0], (f32x4){0.f, 0.f, 0.f, 0.f}, 0, 0, 0); sB[qt] = __builtin_amdgcn_mfma_f32_16x16x32_bf16(Kn[3], Qf[qt][1], sB[qt], 0, 0, 0);
;     }
;     if (DRY != 2) if (on < 27) attn_load_k(pn, C.r4, C.j0, C.rowbase, C.h, C.klo, C.Kr, Kn);
.LBB0_594:
	s_add_i32 s0, s4, 0xfffc
	s_and_b32 s1, s0, 0xff
	s_mulk_i32 s1, 0xab
	s_bfe_u32 s1, s1, 0x70009
	s_mul_i32 s14, s1, 3
	s_sub_i32 s0, s0, s14
	s_mul_i32 s0, s0, 3
	s_add_i32 s0, s1, s0
	s_add_i32 s0, s0, 18
	s_and_b32 s0, s0, 0xff
	s_sub_i32 s0, s0, 18
	s_mul_i32 s14, s0, 0xab
	s_bfe_u32 s14, s14, 0x70009
	s_add_i32 s15, s82, s14
	s_mul_i32 s14, s14, -3
	s_lshl_b32 s1, s83, 12
	s_add_i32 s14, s14, s0
	v_add_u32_e32 v114, s1, v187
	s_xor_b32 s1, s1, 0x1000
	s_and_b32 s15, s15, 3
	s_lshl_b32 s0, s14, 5
	s_add_i32 s1, s59, s1
	s_or_b32 s15, s15, s78
	s_add_i32 s14, s0, s81
	s_add_i32 s0, s0, s79
	s_cmpk_lt_u32 s14, 0x800
	s_cselect_b32 s42, s14, s0
	s_cmpk_lt_u32 s0, 0x800
	s_cselect_b32 s0, s0, s14
	s_lshl_b32 s14, s42, 2
	s_waitcnt vmcnt(3)
	v_mfma_f32_16x16x32_bf16 v[128:131], v[100:103], v[64:67], 0
	s_add_i32 s14, s14, s15
	s_mulk_i32 s14, 0x600
	s_lshl_b32 s0, s0, 2
	s_waitcnt vmcnt(0)
	s_add_i32 s14, s14, s62
	s_add_i32 s0, s0, s15
	s_waitcnt vmcnt(0)
	ds_read_b64_tr_b16 v[124:125], v114
	ds_read_b64_tr_b16 v[120:121], v114 offset:32
	ds_read_b64_tr_b16 v[116:117], v114 offset:1024
	ds_read_b64_tr_b16 v[112:113], v114 offset:1056
	ds_read_b64_tr_b16 v[126:127], v114 offset:2048
	ds_read_b64_tr_b16 v[122:123], v114 offset:2080
	ds_read_b64_tr_b16 v[118:119], v114 offset:3072
	ds_read_b64_tr_b16 v[114:115], v114 offset:3104
	s_lshl_b32 s14, s14, 1
	s_mulk_i32 s0, 0x600
	s_mov_b32 m0, s1
	v_mfma_f32_16x16x32_bf16 v[136:139], v[108:111], v[68:71], v[128:131]
	s_add_i32 s0, s0, s62
	buffer_load_dwordx4 v182, s[8:11], s14 offen lds
	s_add_i32 m0, s1, 0x400
	v_mfma_f32_16x16x32_bf16 v[128:131], v[96:99], v[64:67], 0
	s_lshl_b32 s0, s0, 1
	buffer_load_dwordx4 v186, s[8:11], s14 offen lds
	s_add_i32 m0, s1, 0x800
	v_mfma_f32_16x16x32_bf16 v[100:103], v[100:103], v[72:75], 0
	buffer_load_dwordx4 v182, s[8:11], s0 offen lds
	s_add_i32 m0, s1, 0xc00
	s_mov_b32 s42, s10
	v_mfma_f32_16x16x32_bf16 v[96:99], v[96:99], v[72:75], 0
	buffer_load_dwordx4 v186, s[8:11], s0 offen lds
	s_mov_b32 s43, s11
	v_max_f32_e32 v144, v137, v137
	v_mfma_f32_16x16x32_bf16 v[140:143], v[104:107], v[68:71], v[128:131]
	v_max_f32_e32 v145, v136, v136
	v_max_f32_e32 v144, v145, v144
	v_max_f32_e32 v145, v139, v139
	v_mfma_f32_16x16x32_bf16 v[128:131], v[108:111], v[76:79], v[100:103]
	v_max_f32_e32 v146, v138, v138
	v_max_f32_e32 v145, v146, v145
	s_nop 1
	v_max_f32_e32 v146, v143, v143
	v_mfma_f32_16x16x32_bf16 v[132:135], v[104:107], v[76:79], v[96:99]
	buffer_load_dwordx4 v[100:103], v184, s[40:43], s14 offen
	s_nop 1
	buffer_load_dwordx4 v[96:99], v184, s[40:43], s0 offen
	buffer_load_dwordx4 v[108:111], v185, s[40:43], s14 offen
	buffer_load_dwordx4 v[104:107], v185, s[40:43], s0 offen
	v_max_f32_e32 v147, v142, v142
	v_max_f32_e32 v146, v147, v146
	v_max3_f32 v146, v140, v141, v146
	v_max3_f32 v145, v144, v145, v146
	v_max3_f32 v144, v128, v129, v130
	v_max3_f32 v146, v131, v132, v133
	v_max3_f32 v144, v144, v134, v135
	v_max_f32_e32 v144, v144, v146
	v_add_f32_e32 v146, 0x41000000, v194
	v_cmp_gt_f32_e32 vcc, v145, v146
	v_add_f32_e32 v146, 0x41000000, v193
	v_cmp_gt_f32_e64 s[0:1], v144, v146
	s_or_b64 vcc, vcc, s[0:1]
	s_cbranch_vccz .LBB0_593
	v_mov_b32_e32 v146, v145
	s_nop 1
	v_permlane16_swap_b32_e32 v145, v146
	v_max_f32_e32 v145, v145, v146
	v_mov_b32_e32 v146, v145
	s_nop 1
	v_permlane32_swap_b32_e32 v145, v146
	v_max_f32_e32 v145, v145, v146
	v_mov_b32_e32 v146, v144
	s_nop 1
	v_permlane16_swap_b32_e32 v144, v146
	v_max_f32_e32 v144, v144, v146
	v_mov_b32_e32 v146, v144
	s_nop 1
	v_permlane32_swap_b32_e32 v144, v146
	v_max_f32_e32 v144, v144, v146
	v_max_f32_e32 v145, v145, v145
	v_max_f32_e32 v146, v194, v194
	v_max_f32_e32 v145, v146, v145
	v_sub_f32_e32 v146, v194, v145
	v_exp_f32_e32 v146, v146
	v_max_f32_e32 v144, v144, v144
	v_mov_b32_e32 v194, v145
	v_pk_mul_f32 v[62:63], v[62:63], v[146:147] op_sel_hi:[1,0]
	v_pk_mul_f32 v[60:61], v[60:61], v[146:147] op_sel_hi:[1,0]
	v_pk_mul_f32 v[58:59], v[58:59], v[146:147] op_sel_hi:[1,0]
	v_pk_mul_f32 v[56:57], v[56:57], v[146:147] op_sel_hi:[1,0]
	v_pk_mul_f32 v[54:55], v[54:55], v[146:147] op_sel_hi:[1,0]
	v_pk_mul_f32 v[52:53], v[52:53], v[146:147] op_sel_hi:[1,0]
	v_pk_mul_f32 v[50:51], v[50:51], v[146:147] op_sel_hi:[1,0]
	v_pk_mul_f32 v[48:49], v[48:49], v[146:147] op_sel_hi:[1,0]
	v_max_f32_e32 v147, v193, v193
	v_max_f32_e32 v148, v147, v144
	v_sub_f32_e32 v144, v193, v148
	v_exp_f32_e32 v147, v144
	v_mov_b32_e32 v193, v148
	v_mov_b32_e32 v144, v147
	v_pk_mul_f32 v[178:179], v[178:179], v[146:147]
	v_pk_mul_f32 v[46:47], v[46:47], v[144:145] op_sel_hi:[1,0]
	v_pk_mul_f32 v[44:45], v[44:45], v[144:145] op_sel_hi:[1,0]
	v_pk_mul_f32 v[42:43], v[42:43], v[144:145] op_sel_hi:[1,0]
	v_pk_mul_f32 v[40:41], v[40:41], v[144:145] op_sel_hi:[1,0]
	v_pk_mul_f32 v[38:39], v[38:39], v[144:145] op_sel_hi:[1,0]
	v_pk_mul_f32 v[36:37], v[36:37], v[144:145] op_sel_hi:[1,0]
	v_pk_mul_f32 v[34:35], v[34:35], v[144:145] op_sel_hi:[1,0]
	v_pk_mul_f32 v[32:33], v[32:33], v[144:145] op_sel_hi:[1,0]
	s_branch .LBB0_593

; template <int MODE  , int QLO, int QHI> ...
;     ...
;         for (int qt = QLO; qt < QHI; ++qt) {
;             const float a = fmaxf(fmaxf(fmaxf(sA[qt][0], sA[qt][1]), fmaxf(sA[qt][2], sA[qt][3])), fmaxf(fmaxf(sB[qt][0], sB[qt][1]), fmaxf(sB[qt][2], sB[qt][3])));
;             tmax[qt] = xmax16_32(a);
;         }
;         bool need = false;
; #pragma unroll
;         for (int qt = QLO; qt < QHI; ++qt) need = need || (tmax[qt] > mrun[qt] + 8.f);
;         if (__builtin_amdgcn_ballot_w64(need) != 0ull) {
; #pragma unroll
;             for (int qt = QLO; qt < QHI; ++qt) {
;                 const float mnew = fmaxf(mrun[qt], tmax[qt]); const float alpha = __builtin_amdgcn_exp2f(mrun[qt] - mnew);
;                 mrun[qt] = mnew; lrun[qt] *= alpha;
; #pragma unroll
;                 for (int dt = 0; dt < 4; ++dt) O[qt][dt] = O[qt][dt] * alpha;
;             }
; template <int MODE, int DRY, int QLO, int QHI>
; __device__ __forceinline__ int attn_step(int o, int& par, const AttnCtx& C, const AttnLane& L, f32x4 (&O)[4][4], float (&mrun)[4], float (&lrun)[4], const bf16x8 (&Qf)[4][2], bf16x8 (&Kn)[4]) {
;     ...
;     if (DRY != 2) if (on < 27) attn_dma_v(pn, C.r4, C.j0, C.rowbase, C.h, C.vlo, C.Vr, C.vl + (par ^ 1) * 4096);
;     par ^= 1;
;     if (DRY == 1) {
;         asm volatile("" :: "v"(Kn[0]), "v"(Kn[1]), "v"(Kn[2]), "v"(Kn[3]), "v"(Vf[0]), "v"(Vf[1]), "v"(Vf[2]), "v"(Vf[3]));
;         if (on < 27) attn_load_k(pn, C.r4, C.j0, C.rowbase, C.h, C.klo, C.Kr, Kn);
;         return on;
;     }
;     f32x4 sA[4], sB[4];
; #pragma unroll
;     for (int qt = QLO; qt < QHI; ++qt) {
;         sA[qt] = __builtin_amdgcn_mfma_f32_16x16x32_bf16(Kn[0], Qf[qt][0], (f32x4){0.f, 0.f, 0.f, 0.f}, 0, 0, 0); sA[qt] = __builtin_amdgcn_mfma_f32_16x16x32_bf16(Kn[1], Qf[qt][1], sA[qt], 0, 0, 0);
;         sB[qt] = __builtin_amdgcn_mfma_f32_16x16x32_bf16(Kn[2], Qf[qt][0], (f32x4){0.f, 0.f, 0.f, 0.f}, 0, 0, 0); sB[qt] = __builtin_amdgcn_mfma_f32_16x16x32_bf16(Kn[3], Qf[qt][1], sB[qt], 0, 0, 0);
;     }
;     if (DRY != 2) if (on < 27) attn_load_k(pn, C.r4, C.j0, C.rowbase, C.h, C.klo, C.Kr, Kn);
.LBB0_599:
	s_add_i32 s0, s33, 0xfffc
	s_and_b32 s1, s0, 0xff
	s_mulk_i32 s1, 0xab
	s_bfe_u32 s1, s1, 0x70009
	s_mul_i32 s4, s1, 3
	s_sub_i32 s0, s0, s4
	s_mul_i32 s0, s0, 3
	s_add_i32 s0, s1, s0
	s_add_i32 s0, s0, 18
	s_waitcnt vmcnt(2)
	v_mfma_f32_16x16x32_bf16 v[128:131], v[96:99], v[64:67], 0
	s_and_b32 s0, s0, 0xff
	s_sub_i32 s0, s0, 18
	s_mul_i32 s4, s0, 0xab
	s_waitcnt vmcnt(0)
	v_mfma_f32_16x16x32_bf16 v[156:159], v[104:107], v[68:71], v[128:131]
	s_bfe_u32 s4, s4, 0x70009
	s_add_i32 s5, s82, s4
	s_mul_i32 s4, s4, -3
	v_mfma_f32_16x16x32_bf16 v[128:131], v[100:103], v[72:75], 0
	s_lshl_b32 s1, s83, 12
	s_add_i32 s4, s4, s0
	v_add_u32_e32 v132, s1, v187
	s_xor_b32 s1, s1, 0x1000
	s_and_b32 s5, s5, 3
	s_lshl_b32 s0, s4, 5
	s_add_i32 s1, s59, s1
	v_mfma_f32_16x16x32_bf16 v[144:147], v[108:111], v[76:79], v[128:131]
	s_or_b32 s5, s5, s78
	s_add_i32 s4, s0, s81
	s_add_i32 s0, s0, s79
	v_mfma_f32_16x16x32_bf16 v[128:131], v[96:99], v[72:75], 0
	s_cmpk_lt_u32 s4, 0x800
	s_cselect_b32 s14, s4, s0
	s_cmpk_lt_u32 s0, 0x800
	v_mfma_f32_16x16x32_bf16 v[112:115], v[100:103], v[64:67], 0
	s_cselect_b32 s0, s0, s4
	s_lshl_b32 s4, s14, 2
	s_add_i32 s4, s4, s5
	v_mfma_f32_16x16x32_bf16 v[148:151], v[104:107], v[76:79], v[128:131]
	s_mulk_i32 s4, 0x600
	s_lshl_b32 s0, s0, 2
	s_waitcnt vmcnt(0)
	v_mfma_f32_16x16x32_bf16 v[128:131], v[100:103], v[80:83], 0
	s_add_i32 s4, s4, s62
	s_add_i32 s0, s0, s5
	s_lshl_b32 s4, s4, 1
	v_mfma_f32_16x16x32_bf16 v[152:155], v[108:111], v[68:71], v[112:115]
	ds_read_b64_tr_b16 v[124:125], v132
	ds_read_b64_tr_b16 v[120:121], v132 offset:32
	ds_read_b64_tr_b16 v[116:117], v132 offset:1024
	ds_read_b64_tr_b16 v[112:113], v132 offset:1056
	ds_read_b64_tr_b16 v[126:127], v132 offset:2048
	ds_read_b64_tr_b16 v[122:123], v132 offset:2080
	ds_read_b64_tr_b16 v[118:119], v132 offset:3072
	ds_read_b64_tr_b16 v[114:115], v132 offset:3104
	s_mulk_i32 s0, 0x600
	s_mov_b32 m0, s1
	v_mfma_f32_16x16x32_bf16 v[136:139], v[108:111], v[84:87], v[128:131]
	s_add_i32 s0, s0, s62
	buffer_load_dwordx4 v182, s[8:11], s4 offen lds
	s_add_i32 m0, s1, 0x400
	v_mfma_f32_16x16x32_bf16 v[128:131], v[96:99], v[80:83], 0
	s_lshl_b32 s0, s0, 1
	buffer_load_dwordx4 v186, s[8:11], s4 offen lds
	s_add_i32 m0, s1, 0x800
	v_mfma_f32_16x16x32_bf16 v[100:103], v[100:103], v[88:91], 0
	buffer_load_dwordx4 v182, s[8:11], s0 offen lds
	s_add_i32 m0, s1, 0xc00
	s_mov_b32 s42, s10
	v_mfma_f32_16x16x32_bf16 v[96:99], v[96:99], v[88:91], 0
	buffer_load_dwordx4 v186, s[8:11], s0 offen lds
	s_mov_b32 s43, s11
	v_max_f32_e32 v161, v153, v153
	v_mfma_f32_16x16x32_bf16 v[140:143], v[104:107], v[84:87], v[128:131]
	v_max_f32_e32 v195, v152, v152
	v_max_f32_e32 v161, v195, v161
	v_max_f32_e32 v195, v155, v155
	v_mfma_f32_16x16x32_bf16 v[128:131], v[108:111], v[92:95], v[100:103]
	v_max_f32_e32 v196, v154, v154
	v_max_f32_e32 v195, v196, v195
	v_max_f32_e32 v196, v159, v159
	v_mfma_f32_16x16x32_bf16 v[132:135], v[104:107], v[92:95], v[96:99]
	buffer_load_dwordx4 v[100:103], v184, s[40:43], s4 offen
	s_nop 1
	buffer_load_dwordx4 v[96:99], v184, s[40:43], s0 offen
	buffer_load_dwordx4 v[108:111], v185, s[40:43], s4 offen
	buffer_load_dwordx4 v[104:107], v185, s[40:43], s0 offen
	v_max_f32_e32 v197, v158, v158
	v_max_f32_e32 v196, v197, v196
	v_max3_f32 v196, v156, v157, v196
	v_max3_f32 v197, v161, v195, v196
	v_max3_f32 v161, v144, v145, v146
	v_max3_f32 v195, v147, v148, v149
	v_max3_f32 v161, v161, v150, v151
	v_max_f32_e32 v196, v161, v195
	v_max3_f32 v161, v136, v137, v138
	v_max3_f32 v195, v139, v140, v141
	v_max3_f32 v161, v161, v142, v143
	v_max_f32_e32 v195, v161, v195
	v_max3_f32 v161, v128, v129, v130
	v_max3_f32 v198, v131, v132, v133
	v_max3_f32 v161, v161, v134, v135
	v_max_f32_e32 v161, v161, v198
	v_add_f32_e32 v198, 0x41000000, v194
	v_cmp_gt_f32_e32 vcc, v197, v198
	v_add_f32_e32 v198, 0x41000000, v193
	v_cmp_gt_f32_e64 s[0:1], v196, v198
	v_add_f32_e32 v198, 0x41000000, v192
	s_or_b64 s[0:1], vcc, s[0:1]
	v_cmp_gt_f32_e32 vcc, v195, v198
	v_add_f32_e32 v198, 0x41000000, v167
	s_or_b64 s[0:1], s[0:1], vcc
	v_cmp_gt_f32_e32 vcc, v161, v198
	s_or_b64 vcc, s[0:1], vcc
	s_cbranch_vccz .LBB0_598
; __device__ __forceinline__ float xmax16_32(float a) {
;     { auto rr = __builtin_amdgcn_permlane16_swap(__float_as_uint(a), __float_as_uint(a), false, false); a = fmaxf(__uint_as_float(rr[0]), __uint_as_float(rr[1])); }
;     { auto rr = __builtin_amdgcn_permlane32_swap(__float_as_uint(a), __float_as_uint(a), false, false); a = fmaxf(__uint_as_float(rr[0]), __uint_as_float(rr[1])); }
; template <int MODE  , int QLO, int QHI> ...
;     ...
;             for (int qt = QLO; qt < QHI; ++qt) {
;                 const float mnew = fmaxf(mrun[qt], tmax[qt]); const float alpha = __builtin_amdgcn_exp2f(mrun[qt] - mnew);
;                 mrun[qt] = mnew; lrun[qt] *= alpha;
; #pragma unroll
;                 for (int dt = 0; dt < 4; ++dt) O[qt][dt] = O[qt][dt] * alpha;
;             }
	v_mov_b32_e32 v198, v197
	s_nop 1
	v_permlane16_swap_b32_e32 v197, v198
	v_max_f32_e32 v197, v197, v198
	v_mov_b32_e32 v198, v197
	s_nop 1
	v_permlane32_swap_b32_e32 v197, v198
	v_max_f32_e32 v197, v197, v198
	v_mov_b32_e32 v198, v196
	s_nop 1
	v_permlane16_swap_b32_e32 v196, v198
	v_max_f32_e32 v196, v196, v198
	v_mov_b32_e32 v198, v196
	s_nop 1
	v_permlane32_swap_b32_e32 v196, v198
	v_max_f32_e32 v196, v196, v198
	v_mov_b32_e32 v198, v195
	s_nop 1
	v_permlane16_swap_b32_e32 v195, v198
	v_max_f32_e32 v195, v195, v198
	v_mov_b32_e32 v198, v195
	s_nop 1
	v_permlane32_swap_b32_e32 v195, v198
	v_max_f32_e32 v195, v195, v198
	v_mov_b32_e32 v198, v161
	s_nop 1
	v_permlane16_swap_b32_e32 v161, v198
	v_max_f32_e32 v161, v161, v198
	v_mov_b32_e32 v198, v161
	s_nop 1
	v_permlane32_swap_b32_e32 v161, v198
	v_max_f32_e32 v161, v161, v198
	v_max_f32_e32 v197, v197, v197
	v_max_f32_e32 v198, v194, v194
	v_max_f32_e32 v197, v198, v197
	v_sub_f32_e32 v194, v194, v197
	v_exp_f32_e32 v198, v194
	v_max_f32_e32 v194, v196, v196
	v_max_f32_e32 v196, v193, v193
	v_max_f32_e32 v196, v196, v194
	v_sub_f32_e32 v193, v193, v196
	v_pk_mul_f32 v[62:63], v[62:63], v[198:199] op_sel_hi:[1,0]
	v_pk_mul_f32 v[60:61], v[60:61], v[198:199] op_sel_hi:[1,0]
	v_pk_mul_f32 v[58:59], v[58:59], v[198:199] op_sel_hi:[1,0]
	v_pk_mul_f32 v[56:57], v[56:57], v[198:199] op_sel_hi:[1,0]
	v_pk_mul_f32 v[54:55], v[54:55], v[198:199] op_sel_hi:[1,0]
	v_pk_mul_f32 v[52:53], v[52:53], v[198:199] op_sel_hi:[1,0]
	v_pk_mul_f32 v[50:51], v[50:51], v[198:199] op_sel_hi:[1,0]
	v_pk_mul_f32 v[48:49], v[48:49], v[198:199] op_sel_hi:[1,0]
	v_exp_f32_e32 v199, v193
	v_max_f32_e32 v193, v195, v195
	v_max_f32_e32 v161, v161, v161
	v_mov_b32_e32 v194, v199
	v_pk_mul_f32 v[46:47], v[46:47], v[194:195] op_sel_hi:[1,0]
	v_pk_mul_f32 v[44:45], v[44:45], v[194:195] op_sel_hi:[1,0]
	v_max_f32_e32 v195, v192, v192
	v_max_f32_e32 v195, v195, v193
	v_sub_f32_e32 v192, v192, v195
	v_exp_f32_e32 v192, v192
	v_pk_mul_f32 v[178:179], v[178:179], v[198:199]
	v_pk_mul_f32 v[42:43], v[42:43], v[194:195] op_sel_hi:[1,0]
	v_pk_mul_f32 v[40:41], v[40:41], v[194:195] op_sel_hi:[1,0]
	v_pk_mul_f32 v[30:31], v[30:31], v[192:193] op_sel_hi:[1,0]
	v_pk_mul_f32 v[28:29], v[28:29], v[192:193] op_sel_hi:[1,0]
	v_pk_mul_f32 v[26:27], v[26:27], v[192:193] op_sel_hi:[1,0]
	v_pk_mul_f32 v[24:25], v[24:25], v[192:193] op_sel_hi:[1,0]
	v_pk_mul_f32 v[22:23], v[22:23], v[192:193] op_sel_hi:[1,0]
	v_pk_mul_f32 v[20:21], v[20:21], v[192:193] op_sel_hi:[1,0]
	v_pk_mul_f32 v[18:19], v[18:19], v[192:193] op_sel_hi:[1,0]
	v_pk_mul_f32 v[16:17], v[16:17], v[192:193] op_sel_hi:[1,0]
	v_max_f32_e32 v193, v167, v167
	v_max_f32_e32 v161, v193, v161
	v_sub_f32_e32 v167, v167, v161
	v_exp_f32_e32 v193, v167
	v_pk_mul_f32 v[38:39], v[38:39], v[194:195] op_sel_hi:[1,0]
	v_pk_mul_f32 v[36:37], v[36:37], v[194:195] op_sel_hi:[1,0]
	v_pk_mul_f32 v[34:35], v[34:35], v[194:195] op_sel_hi:[1,0]
	v_pk_mul_f32 v[170:171], v[170:171], v[192:193]
	v_mov_b32_e32 v192, v193
	v_pk_mul_f32 v[32:33], v[32:33], v[194:195] op_sel_hi:[1,0]
	v_pk_mul_f32 v[14:15], v[14:15], v[192:193] op_sel_hi:[1,0]
	v_pk_mul_f32 v[12:13], v[12:13], v[192:193] op_sel_hi:[1,0]
	v_pk_mul_f32 v[10:11], v[10:11], v[192:193] op_sel_hi:[1,0]
	v_pk_mul_f32 v[8:9], v[8:9], v[192:193] op_sel_hi:[1,0]
	v_pk_mul_f32 v[6:7], v[6:7], v[192:193] op_sel_hi:[1,0]
	v_pk_mul_f32 v[4:5], v[4:5], v[192:193] op_sel_hi:[1,0]
	v_pk_mul_f32 v[2:3], v[2:3], v[192:193] op_sel_hi:[1,0]
	v_pk_mul_f32 v[0:1], v[0:1], v[192:193] op_sel_hi:[1,0]
	v_mov_b32_e32 v167, v161
	v_mov_b32_e32 v192, v195
	v_mov_b32_e32 v193, v196
	v_mov_b32_e32 v194, v197
	s_branch .LBB0_598

; template <int MODE  , int QLO, int QHI> ...
;     ...
;         float vsA[4], vsB[4], cA[4], cB[4], tmax[4];
; #pragma unroll
;         for (int qt = QLO; qt < QHI; ++qt) {
;             const int TA = jtA - (j0 + 16 * qt), TB = TA + 16;
;             const bool rA = vA && TA >= -256 && TA <= 256, rB = vB && TB >= -256 && TB <= 256;
;             const int ixA = (TA + 256) >> 4;
;             cA[qt] = cfar[(rA ? ixA : 33) * 64 + lane]; cB[qt] = cfar[(rB ? ixA + 1 : 33) * 64 + lane];
;             vsA[qt] = L.s0 ? sA[qt][0] : (L.s1 ? sA[qt][1] : (L.s2 ? sA[qt][2] : sA[qt][3]));
;             vsB[qt] = L.s0 ? sB[qt][0] : (L.s1 ? sB[qt][1] : (L.s2 ? sB[qt][2] : sB[qt][3]));
;             tmax[qt] = xmax16_32(fmaxf(vsA[qt], vsB[qt]));
;         }
;         bool need = false;
; #pragma unroll
;         for (int qt = QLO; qt < QHI; ++qt) need = need || (tmax[qt] > mrun[qt] + 8.f);
;         if (__builtin_amdgcn_ballot_w64(need) != 0ull) {
.LBB0_634:
	s_cmp_lt_u32 s66, 21
	s_cselect_b32 s0, -15, -9
	s_add_i32 s58, s0, s66
	s_lshl_b32 s64, s58, 5
	s_add_i32 s0, s64, s80
	s_cmpk_lt_u32 s0, 0x800
	s_cselect_b64 s[42:43], -1, 0
	s_sub_i32 s14, s0, s79
	s_add_i32 s0, s14, 0x100
	s_cmpk_lt_u32 s0, 0x201
	s_cselect_b64 s[0:1], -1, 0
	s_and_b64 s[0:1], s[42:43], s[0:1]
	s_add_i32 s4, s14, 0x110
	s_cmpk_lt_u32 s4, 0x201
	s_cselect_b64 s[4:5], -1, 0
	s_lshl_b32 s14, s14, 2
	s_and_b64 s[4:5], s[42:43], s[4:5]
	s_add_i32 s15, s14, 0x400
	s_and_b64 s[0:1], s[0:1], exec
	s_cselect_b32 s0, s15, 0x840
	s_addk_i32 s14, 0x440
	v_lshl_add_u32 v161, s0, 2, v190
	s_and_b64 s[0:1], s[4:5], exec
	s_cselect_b32 s0, s14, 0x840
	v_cmp_eq_u32_e32 vcc, 1, v162
	v_lshl_add_u32 v195, s0, 2, v190
	v_cmp_eq_u32_e64 s[0:1], 2, v162
	v_cndmask_b32_e32 v156, v156, v157, vcc
	v_cndmask_b32_e32 v152, v152, v153, vcc
	v_cndmask_b32_e64 v156, v156, v158, s[0:1]
	v_cmp_eq_u32_e64 s[4:5], 3, v162
	v_cndmask_b32_e64 v152, v152, v154, s[0:1]
	s_add_i32 s14, s64, -16
	v_cndmask_b32_e64 v156, v156, v159, s[4:5]
	v_cndmask_b32_e64 v152, v152, v155, s[4:5]
	v_max_f32_e32 v153, v156, v152
	s_cmpk_lt_u32 s14, 0x201
	s_cselect_b64 s[14:15], -1, 0
	s_and_b64 s[14:15], s[42:43], s[14:15]
	s_cmp_lt_u32 s58, 17
	s_cselect_b64 s[48:49], -1, 0
	s_lshl_b32 s58, s58, 7
	s_and_b64 s[48:49], s[48:49], s[42:43]
	s_sub_i32 s65, s58, 64
	s_and_b64 s[14:15], s[14:15], exec
	s_cselect_b32 s14, s65, 0x840
	v_lshl_add_u32 v154, s14, 2, v190
	s_and_b64 s[14:15], s[48:49], exec
	s_cselect_b32 s14, s58, 0x840
	v_lshl_add_u32 v155, s14, 2, v190
	s_sub_i32 s14, s64, 32
	v_cndmask_b32_e32 v148, v148, v149, vcc
	v_cndmask_b32_e32 v144, v144, v145, vcc
	s_cmpk_lt_u32 s14, 0x201
	v_cndmask_b32_e32 v140, v140, v141, vcc
	v_cndmask_b32_e32 v136, v136, v137, vcc
	v_cndmask_b32_e64 v148, v148, v150, s[0:1]
	v_cndmask_b32_e64 v144, v144, v146, s[0:1]
	s_cselect_b64 s[14:15], -1, 0
	v_cndmask_b32_e64 v140, v140, v142, s[0:1]
	v_cndmask_b32_e64 v136, v136, v138, s[0:1]
	v_cndmask_b32_e64 v148, v148, v151, s[4:5]
	v_cndmask_b32_e64 v144, v144, v147, s[4:5]
	s_and_b64 s[14:15], s[42:43], s[14:15]
	s_add_i32 s48, s58, 0xffffff80
	v_cndmask_b32_e64 v142, v140, v143, s[4:5]
	v_cndmask_b32_e64 v143, v136, v139, s[4:5]
	s_and_b64 s[14:15], s[14:15], exec
	v_cndmask_b32_e32 v128, v128, v129, vcc
	v_cndmask_b32_e32 v129, v132, v133, vcc
	v_max_f32_e32 v146, v148, v144
	s_cselect_b32 s14, s48, 0x840
	v_max_f32_e32 v145, v142, v143
	v_cndmask_b32_e64 v128, v128, v130, s[0:1]
	v_cndmask_b32_e64 v129, v129, v134, s[0:1]
	v_lshl_add_u32 v147, s14, 2, v190
	s_sub_i32 s14, s64, 48
	v_cndmask_b32_e64 v128, v128, v131, s[4:5]
	v_cndmask_b32_e64 v129, v129, v135, s[4:5]
	s_cmpk_lt_u32 s14, 0x201
	s_cselect_b64 s[14:15], -1, 0
	v_max_f32_e32 v130, v128, v129
	s_and_b64 s[14:15], s[42:43], s[14:15]
	s_addk_i32 s58, 0xff40
	s_and_b64 s[14:15], s[14:15], exec
	s_cselect_b32 s14, s58, 0x840
	v_lshl_add_u32 v139, s14, 2, v190
	ds_read_b32 v136, v161
	ds_read_b32 v140, v195
	ds_read_b32 v137, v154
	ds_read_b32 v141, v155
	ds_read_b32 v138, v147
	ds_read_b32 v139, v139
	v_add_f32_e32 v131, 0x41000000, v194
	v_cmp_gt_f32_e32 vcc, v153, v131
	v_add_f32_e32 v131, 0x41000000, v193
	v_cmp_gt_f32_e64 s[0:1], v146, v131
	v_add_f32_e32 v131, 0x41000000, v192
	s_or_b64 s[0:1], vcc, s[0:1]
	v_cmp_gt_f32_e32 vcc, v145, v131
	v_add_f32_e32 v131, 0x41000000, v167
	s_or_b64 s[0:1], s[0:1], vcc
	v_cmp_gt_f32_e32 vcc, v130, v131
	s_or_b64 vcc, s[0:1], vcc
	s_cbranch_vccz .LBB0_636
; __device__ __forceinline__ float xmax16_32(float a) {
;     { auto rr = __builtin_amdgcn_permlane16_swap(__float_as_uint(a), __float_as_uint(a), false, false); a = fmaxf(__uint_as_float(rr[0]), __uint_as_float(rr[1])); }
;     { auto rr = __builtin_amdgcn_permlane32_swap(__float_as_uint(a), __float_as_uint(a), false, false); a = fmaxf(__uint_as_float(rr[0]), __uint_as_float(rr[1])); }
; template <int MODE  , int QLO, int QHI> ...
;     ...
;         if (__builtin_amdgcn_ballot_w64(need) != 0ull) {
; #pragma unroll
;             for (int qt = QLO; qt < QHI; ++qt) {
;                 const float mnew = fmaxf(mrun[qt], tmax[qt]); const float alpha = __builtin_amdgcn_exp2f(mrun[qt] - mnew);
;                 mrun[qt] = mnew; lrun[qt] *= alpha;
; #pragma unroll
;                 for (int dt = 0; dt < 4; ++dt) O[qt][dt] = O[qt][dt] * alpha;
;             }
;         }
	v_mov_b32_e32 v131, v153
	s_nop 1
	v_permlane16_swap_b32_e32 v153, v131
	v_max_f32_e32 v153, v153, v131
	v_mov_b32_e32 v131, v153
	s_nop 1
	v_permlane32_swap_b32_e32 v153, v131
	v_max_f32_e32 v153, v153, v131
	v_mov_b32_e32 v131, v146
	s_nop 1
	v_permlane16_swap_b32_e32 v146, v131
	v_max_f32_e32 v146, v146, v131
	v_mov_b32_e32 v131, v146
	s_nop 1
	v_permlane32_swap_b32_e32 v146, v131
	v_max_f32_e32 v146, v146, v131
	v_mov_b32_e32 v131, v145
	s_nop 1
	v_permlane16_swap_b32_e32 v145, v131
	v_max_f32_e32 v145, v145, v131
	v_mov_b32_e32 v131, v145
	s_nop 1
	v_permlane32_swap_b32_e32 v145, v131
	v_max_f32_e32 v145, v145, v131
	v_mov_b32_e32 v131, v130
	s_nop 1
	v_permlane16_swap_b32_e32 v130, v131
	v_max_f32_e32 v130, v130, v131
	v_mov_b32_e32 v131, v130
	s_nop 1
	v_permlane32_swap_b32_e32 v130, v131
	v_max_f32_e32 v130, v130, v131
	v_max_f32_e32 v131, v153, v153
	v_max_f32_e32 v132, v194, v194
	v_max_f32_e32 v131, v132, v131
	v_sub_f32_e32 v132, v194, v131
	v_exp_f32_e32 v132, v132
	v_max_f32_e32 v134, v193, v193
	v_max_f32_e32 v130, v130, v130
	v_mov_b32_e32 v194, v131
	v_pk_mul_f32 v[62:63], v[62:63], v[132:133] op_sel_hi:[1,0]
	v_pk_mul_f32 v[60:61], v[60:61], v[132:133] op_sel_hi:[1,0]
	v_pk_mul_f32 v[58:59], v[58:59], v[132:133] op_sel_hi:[1,0]
	v_pk_mul_f32 v[56:57], v[56:57], v[132:133] op_sel_hi:[1,0]
	v_pk_mul_f32 v[54:55], v[54:55], v[132:133] op_sel_hi:[1,0]
	v_pk_mul_f32 v[52:53], v[52:53], v[132:133] op_sel_hi:[1,0]
	v_pk_mul_f32 v[50:51], v[50:51], v[132:133] op_sel_hi:[1,0]
	v_pk_mul_f32 v[48:49], v[48:49], v[132:133] op_sel_hi:[1,0]
	v_max_f32_e32 v133, v146, v146
	v_max_f32_e32 v146, v134, v133
	v_sub_f32_e32 v133, v193, v146
	v_exp_f32_e32 v133, v133
	v_max_f32_e32 v134, v192, v192
	v_mov_b32_e32 v193, v146
	v_pk_mul_f32 v[178:179], v[178:179], v[132:133]
	v_mov_b32_e32 v132, v133
	v_pk_mul_f32 v[46:47], v[46:47], v[132:133] op_sel_hi:[1,0]
	v_pk_mul_f32 v[44:45], v[44:45], v[132:133] op_sel_hi:[1,0]
	v_max_f32_e32 v133, v145, v145
	v_max_f32_e32 v133, v134, v133
	v_sub_f32_e32 v134, v192, v133
	v_exp_f32_e32 v134, v134
	v_pk_mul_f32 v[42:43], v[42:43], v[132:133] op_sel_hi:[1,0]
	v_pk_mul_f32 v[40:41], v[40:41], v[132:133] op_sel_hi:[1,0]
	v_pk_mul_f32 v[38:39], v[38:39], v[132:133] op_sel_hi:[1,0]
	v_pk_mul_f32 v[30:31], v[30:31], v[134:135] op_sel_hi:[1,0]
	v_pk_mul_f32 v[28:29], v[28:29], v[134:135] op_sel_hi:[1,0]
	v_pk_mul_f32 v[26:27], v[26:27], v[134:135] op_sel_hi:[1,0]
	v_pk_mul_f32 v[24:25], v[24:25], v[134:135] op_sel_hi:[1,0]
	v_pk_mul_f32 v[22:23], v[22:23], v[134:135] op_sel_hi:[1,0]
	v_pk_mul_f32 v[20:21], v[20:21], v[134:135] op_sel_hi:[1,0]
	v_pk_mul_f32 v[18:19], v[18:19], v[134:135] op_sel_hi:[1,0]
	v_pk_mul_f32 v[16:17], v[16:17], v[134:135] op_sel_hi:[1,0]
	v_max_f32_e32 v135, v167, v167
	v_max_f32_e32 v145, v135, v130
	v_sub_f32_e32 v130, v167, v145
	v_exp_f32_e32 v135, v130
	v_pk_mul_f32 v[36:37], v[36:37], v[132:133] op_sel_hi:[1,0]
	v_pk_mul_f32 v[34:35], v[34:35], v[132:133] op_sel_hi:[1,0]
	v_pk_mul_f32 v[32:33], v[32:33], v[132:133] op_sel_hi:[1,0]
	v_mov_b32_e32 v130, v135
	v_pk_mul_f32 v[170:171], v[170:171], v[134:135]
	v_pk_mul_f32 v[14:15], v[14:15], v[130:131] op_sel_hi:[1,0]
	v_pk_mul_f32 v[12:13], v[12:13], v[130:131] op_sel_hi:[1,0]
	v_pk_mul_f32 v[10:11], v[10:11], v[130:131] op_sel_hi:[1,0]
	v_pk_mul_f32 v[8:9], v[8:9], v[130:131] op_sel_hi:[1,0]
	v_pk_mul_f32 v[6:7], v[6:7], v[130:131] op_sel_hi:[1,0]
	v_pk_mul_f32 v[4:5], v[4:5], v[130:131] op_sel_hi:[1,0]
	v_pk_mul_f32 v[2:3], v[2:3], v[130:131] op_sel_hi:[1,0]
	v_pk_mul_f32 v[0:1], v[0:1], v[130:131] op_sel_hi:[1,0]
	v_mov_b32_e32 v167, v145
	v_mov_b32_e32 v192, v133

; __device__ __forceinline__ float xmax16_32(float a) {
;     { auto rr = __builtin_amdgcn_permlane16_swap(__float_as_uint(a), __float_as_uint(a), false, false); a = fmaxf(__uint_as_float(rr[0]), __uint_as_float(rr[1])); }
;     { auto rr = __builtin_amdgcn_permlane32_swap(__float_as_uint(a), __float_as_uint(a), false, false); a = fmaxf(__uint_as_float(rr[0]), __uint_as_float(rr[1])); }
; template <int MODE  , int QLO, int QHI> ...
;     ...
;         float tmax[4];
; #pragma unroll
;         for (int qt = QLO; qt < QHI; ++qt) {
;             const float a = fmaxf(fmaxf(fmaxf(sA[qt][0], sA[qt][1]), fmaxf(sA[qt][2], sA[qt][3])), fmaxf(fmaxf(sB[qt][0], sB[qt][1]), fmaxf(sB[qt][2], sB[qt][3])));
;             tmax[qt] = xmax16_32(a);
;         }
;         bool need = false;
; #pragma unroll
;         for (int qt = QLO; qt < QHI; ++qt) need = need || (tmax[qt] > mrun[qt] + 8.f);
;         if (__builtin_amdgcn_ballot_w64(need) != 0ull) {
; #pragma unroll
;             for (int qt = QLO; qt < QHI; ++qt) {
;                 const float mnew = fmaxf(mrun[qt], tmax[qt]); const float alpha = __builtin_amdgcn_exp2f(mrun[qt] - mnew);
;                 mrun[qt] = mnew; lrun[qt] *= alpha;
; #pragma unroll
;                 for (int dt = 0; dt < 4; ++dt) O[qt][dt] = O[qt][dt] * alpha;
;             }
;         }
.LBB0_690:
	s_nop 1
	v_max3_f32 v144, v136, v137, v138
	v_max3_f32 v145, v139, v140, v141
	v_max3_f32 v144, v144, v142, v143
	v_max_f32_e32 v145, v144, v145
	v_max3_f32 v144, v128, v129, v130
	v_max3_f32 v146, v131, v132, v133
	v_max3_f32 v144, v144, v134, v135
	v_max_f32_e32 v144, v144, v146
	v_add_f32_e32 v146, 0x41000000, v192
	v_cmp_gt_f32_e32 vcc, v145, v146
	v_add_f32_e32 v146, 0x41000000, v167
	v_cmp_gt_f32_e64 s[0:1], v144, v146
	s_or_b64 vcc, vcc, s[0:1]
	s_cbranch_vccz .LBB0_692
	v_mov_b32_e32 v146, v145
	s_nop 1
	v_permlane16_swap_b32_e32 v145, v146
	v_max_f32_e32 v145, v145, v146
	v_mov_b32_e32 v146, v145
	s_nop 1
	v_permlane32_swap_b32_e32 v145, v146
	v_max_f32_e32 v145, v145, v146
	v_mov_b32_e32 v146, v144
	s_nop 1
	v_permlane16_swap_b32_e32 v144, v146
	v_max_f32_e32 v144, v144, v146
	v_mov_b32_e32 v146, v144
	s_nop 1
	v_permlane32_swap_b32_e32 v144, v146
	v_max_f32_e32 v144, v144, v146
	v_max_f32_e32 v145, v145, v145
	v_max_f32_e32 v146, v192, v192
	v_max_f32_e32 v145, v146, v145
	v_sub_f32_e32 v146, v192, v145
	v_exp_f32_e32 v146, v146
	v_max_f32_e32 v144, v144, v144
	v_mov_b32_e32 v192, v145
	v_pk_mul_f32 v[30:31], v[30:31], v[146:147] op_sel_hi:[1,0]
	v_pk_mul_f32 v[28:29], v[28:29], v[146:147] op_sel_hi:[1,0]
	v_pk_mul_f32 v[26:27], v[26:27], v[146:147] op_sel_hi:[1,0]
	v_pk_mul_f32 v[24:25], v[24:25], v[146:147] op_sel_hi:[1,0]
	v_pk_mul_f32 v[22:23], v[22:23], v[146:147] op_sel_hi:[1,0]
	v_pk_mul_f32 v[20:21], v[20:21], v[146:147] op_sel_hi:[1,0]
	v_pk_mul_f32 v[18:19], v[18:19], v[146:147] op_sel_hi:[1,0]
	v_pk_mul_f32 v[16:17], v[16:17], v[146:147] op_sel_hi:[1,0]
	v_max_f32_e32 v147, v167, v167
	v_max_f32_e32 v148, v147, v144
	v_sub_f32_e32 v144, v167, v148
	v_exp_f32_e32 v147, v144
	v_mov_b32_e32 v167, v148
	v_mov_b32_e32 v144, v147
	v_pk_mul_f32 v[170:171], v[170:171], v[146:147]
	v_pk_mul_f32 v[14:15], v[14:15], v[144:145] op_sel_hi:[1,0]
	v_pk_mul_f32 v[12:13], v[12:13], v[144:145] op_sel_hi:[1,0]
	v_pk_mul_f32 v[10:11], v[10:11], v[144:145] op_sel_hi:[1,0]
	v_pk_mul_f32 v[8:9], v[8:9], v[144:145] op_sel_hi:[1,0]
	v_pk_mul_f32 v[6:7], v[6:7], v[144:145] op_sel_hi:[1,0]
	v_pk_mul_f32 v[4:5], v[4:5], v[144:145] op_sel_hi:[1,0]
	v_pk_mul_f32 v[2:3], v[2:3], v[144:145] op_sel_hi:[1,0]
	v_pk_mul_f32 v[0:1], v[0:1], v[144:145] op_sel_hi:[1,0]
